# dn_pre A tiles: per-tile LDS reads (fragments, gc/beta as b128) issued together, masks by cndmask, one b128 store (was 7 exposed LDS round trips per tile)
# baseline (speedup 1.0000x reference)
.LBB0_405:
	s_add_i32 s2, s20, 4
	s_cmp_gt_i32 s20, 5
	s_mov_b32 s20, s2
	s_cbranch_scc1 .LBB0_417

.LBB0_409:
	s_sub_i32 s2, s20, s36
	v_or_b32_e32 v4, s21, v3
	s_movk_i32 s1, 0x90
	v_mad_u64_u32 v[14:15], s[36:37], v4, s1, v[8:9]
	v_lshl_or_b32 v9, s2, 4, v3
	v_mad_u64_u32 v[16:17], s[36:37], v9, s1, v[8:9]
	v_or_b32_e32 v11, s21, v31
	v_lshlrev_b32_e32 v12, 2, v11
	v_lshlrev_b32_e32 v10, 2, v9
	ds_read_b128 v[80:83], v14 offset:55808
	ds_read_b128 v[84:87], v16 offset:55808
	ds_read_b128 v[88:91], v14 offset:55872
	ds_read_b128 v[92:95], v16 offset:55872
	ds_read_b32 v104, v10 offset:55296
	ds_read_b128 v[96:99], v12 offset:55296
	ds_read_b128 v[100:103], v12 offset:55552
	s_movk_i32 s1, 0x110
	v_mul_lo_u32 v13, v9, s1
	v_lshl_add_u32 v13, v11, 2, v13
	s_waitcnt lgkmcnt(3)
	v_mfma_f32_16x16x32_bf16 v[4:7], v[80:83], v[84:87], 0
	v_mfma_f32_16x16x32_bf16 v[4:7], v[88:91], v[92:95], v[4:7]
	s_waitcnt lgkmcnt(0)
	v_sub_f32_e32 v96, v96, v104
	v_sub_f32_e32 v97, v97, v104
	v_sub_f32_e32 v98, v98, v104
	v_sub_f32_e32 v99, v99, v104
	v_mul_f32_e32 v96, 0x3fb8aa3b, v96
	v_mul_f32_e32 v97, 0x3fb8aa3b, v97
	v_mul_f32_e32 v98, 0x3fb8aa3b, v98
	v_mul_f32_e32 v99, 0x3fb8aa3b, v99
	v_exp_f32_e32 v96, v96
	v_exp_f32_e32 v97, v97
	v_exp_f32_e32 v98, v98
	v_exp_f32_e32 v99, v99
	v_or_b32_e32 v14, 2, v11
	v_or_b32_e32 v15, 3, v11
	v_cmp_gt_i32_e64 s[36:37], v11, v9
	v_cmp_ge_i32_e64 s[38:39], v11, v9
	v_mul_f32_e32 v4, v4, v100
	v_mul_f32_e32 v5, v5, v101
	v_mul_f32_e32 v6, v6, v102
	v_mul_f32_e32 v7, v7, v103
	v_mul_f32_e32 v4, v4, v96
	v_mul_f32_e32 v5, v5, v97
	v_mul_f32_e32 v6, v6, v98
	v_mul_f32_e32 v7, v7, v99
	v_cndmask_b32_e64 v108, 0, v4, s[36:37]
	v_cndmask_b32_e64 v109, 0, v5, s[38:39]
	v_cmp_gt_i32_e64 s[36:37], v14, v9
	v_cmp_gt_i32_e64 s[38:39], v15, v9
	s_nop 1
	v_cndmask_b32_e64 v110, 0, v6, s[36:37]
	v_cndmask_b32_e64 v111, 0, v7, s[38:39]
	ds_write_b128 v13, v[108:111] offset:33792
	s_branch .LBB0_405
